# P2: waves 4-7 start each item's tasks half a task late (s_sleep) so the two waves of a SIMD run different task phases
# baseline (speedup 1.0000x reference)
; #define ATT_QPTR(I, i_) (Z + ((size_t)((I).qslot0() + ((I).isA ? ((wave * 4 + (i_)) >> 3) : 0)) * TT + (I).seq0 + (I).res * (I).Lr + (I).j0 + 16 * ATT_QT(I, i_) + qi) * 64)
;     ...
;         const int ntask = cur.isA ? 4 : 2;
;     ...
;         if (wave >= 4) { if (cur.isA) __builtin_amdgcn_s_sleep(ATT_DEPHASE); else __builtin_amdgcn_s_sleep((ATT_DEPHASE * 5) / 8); }
;     ...
; #pragma unroll 1
;         for (int i = 0; i < ntask; ++i) {
;             const int qt = ATT_QT(cur, i); const bool lastt = (i + 1 == ntask);
;             const bf16* nq = lastt ? ATT_QPTR(nxt, 0) : ATT_QPTR(cur, i + 1);
;             const bool has_nq = !lastt || more;
;             if (cur.isA) { const int h = (wave * 4 + i) >> 3, habs = cur.hs * 4 + h; const int qtok = cur.seq0 + cur.j0 + 16 * qt + qi; const int ks = qt < 6 ? 16 * qt : 96;
;                 attn_task<9, true>(ldsK, ldsV, tbl + h * TBL, pmt, ks, q0, q1, nq, has_nq, cur.n() + 16 * qt + qi, sink[habs] * LOG2E, (bf16*)((unsigned char*)OA + (size_t)qtok * 768 + habs * 64), nullptr, qi, g, abl);
;             } else { const int jj = cur.j0 + 16 * qt + qi; const int jr = cur.pair ? (jj & (cur.Lr - 1)) : jj, rs = cur.res + (cur.pair ? (jj / cur.Lr) : 0);
;                 const int qtok = cur.seq0 + jr * cur.dil + rs; const int ks = qt < 14 ? 16 * qt : 224;
;                 attn_task<5, false>(ldsK, ldsV, tbl, pmt + (qt >> 3) * NKS_MAX, ks, q0, q1, nq, has_nq, cur.n() + 16 * qt + qi, 0.f, OBG + ((size_t)(cur.hs >> 2) * TT + qtok) * 256 + (cur.hs & 3) * 64, LSE + ((size_t)(cur.hs >> 2) * TT + qtok) * 4 + (cur.hs & 3), qi, g, abl);
.LBB0_238:
	s_and_b64 s[58:59], s[50:51], exec
	s_cselect_b32 s88, 2, 4
	s_lshl_b32 s1, s67, 2
	s_add_i32 s58, s67, 12
	s_add_i32 s1, s1, s71
	s_ashr_i32 s59, s69, 31
	s_ashr_i32 s60, s65, 31
	s_ashr_i32 s61, s86, 31
	s_cmp_eq_u32 s70, 0
	s_cselect_b32 s1, s58, s1
	s_cselect_b32 s58, s73, s72
	s_ashr_i32 s63, s58, 31
	s_add_u32 s64, s86, s65
	s_addc_u32 s60, s61, s60
	s_add_u32 s61, s64, s69
	s_addc_u32 s59, s60, s59
	s_add_u32 s58, s61, s58
	s_mul_hi_i32 s62, s1, 0x14000
	s_mul_i32 s1, s1, 0x14000
	s_addc_u32 s59, s59, s63
	s_add_u32 s58, s58, s1
	s_addc_u32 s59, s59, s62
	s_lshl_b32 s89, s46, 2
	s_add_i32 s90, s46, 12
	s_ashr_i32 s1, s97, 31
	s_ashr_i32 s62, s0, 31
	s_ashr_i32 s63, s99, 31
	s_add_i32 s60, s98, -1
	s_and_b64 s[6:7], s[6:7], exec
	s_cselect_b32 s91, -1, s60
	s_and_b32 s7, s46, 3
	s_add_i32 s92, s92, s97
	s_ashr_i32 s6, s46, 2
	s_lshl_b32 s46, s7, 2
	s_add_u32 s60, s14, s46
	s_addc_u32 s61, s15, 0
	s_lshl_b32 s46, s7, 7
	s_add_u32 s7, s99, s97
	s_addc_u32 s1, s63, s1
	s_add_u32 s93, s7, s0
	s_addc_u32 s94, s1, s62
	s_abs_i32 s95, s98
	v_cvt_f32_u32_e32 v0, s95
	s_sub_i32 s0, 0, s95
	v_add_u32_e32 v57, s99, v144
	v_rcp_iflag_f32_e32 v0, v0
	s_mov_b32 s96, 0
	v_add_u32_e32 v201, s97, v57
	s_mul_hi_i32 s63, s6, 0x14000
	v_mul_f32_e32 v0, 0x4f7ffffe, v0
	v_cvt_u32_f32_e32 v0, v0
	s_mul_i32 s62, s6, 0x14000
	v_lshl_add_u64 v[22:23], v[152:153], 0, s[46:47]
	s_ashr_i32 s46, s98, 31
	v_mul_lo_u32 v1, s0, v0
	v_mul_hi_u32 v1, v0, v1
	v_add_u32_e32 v202, v0, v1
	s_add_i32 s97, s88, -1
	s_mov_b32 s98, s73
	v_mov_b32_e32 v203, v190
	s_cmp_lt_u32 s77, 16
	s_cbranch_scc1 .Lmy_nodeph
	s_cmp_eq_u32 s88, 2
	s_cbranch_scc1 .Lmy_deph_b
	s_sleep 47
	s_branch .Lmy_nodeph
.Lmy_deph_b:
	s_sleep 27
.Lmy_nodeph:
	s_branch .LBB0_241
.LBB0_239:
	s_or_b64 exec, exec, s[6:7]
	s_waitcnt vmcnt(5)
	v_mov_b64_e32 v[110:111], v[2:3]
	s_waitcnt vmcnt(4)
	v_mov_b64_e32 v[114:115], v[6:7]
	v_mov_b64_e32 v[108:109], v[0:1]
	v_mov_b64_e32 v[112:113], v[4:5]
